# prompt attention loop: static s_setprio 1 for waves 4-7 during the tile loop
# baseline (speedup 1.0000x reference)
; #define LAS __attribute__((address_space(3)))
; __device__ __forceinline__ void attn_unit(const Args& a, LAS unsigned char* lds, const int mode, const int h, const int qb, const int tid_in, const int lane_in, const int wave) {
;     ...
;     float m_run = -INFINITY, l_run = 0.f, cqm = 0.f; f32x16 o0 = {}, o1 = {};
;     ...
;     tile_load(jstart); tile_write(jstart, 0); __syncthreads();
;     for (int j = jstart; j < NT; ++j) {
;         const int buf = (j - jstart) & 1;
;         if (j + 1 < NT) tile_load(j + 1);
;         const int kp0 = j * 64;
;         if (active && kp0 <= qfirst + 31) {
;             attn_tile(lds + AT_K + buf * AT_KB, lds + AT_V + buf * AT_VB, (const LAS f32x4*)(lds + AT_CK + buf * 256), qr, cq2, kp0, qpos, qfirst, lane, r32, hi, m_run, l_run, cqm, o0, o1);
.LBB0_516:
	s_or_b64 exec, exec, s[0:1]
	v_mul_lo_u32 v5, v2, s25
	v_lshlrev_b32_e32 v4, 4, v4
	v_add3_u32 v91, 0, v5, v4
	v_lshl_add_u32 v95, v2, 4, v91
	v_lshl_add_u32 v96, v1, 2, 0
	s_waitcnt vmcnt(1)
	ds_write_b128 v91, v[82:85]
	s_waitcnt vmcnt(0)
	ds_write_b128 v95, v[86:89] offset:18432
	s_and_saveexec_b64 s[0:1], s[2:3]
	ds_write_b32 v96, v97 offset:38912
	s_or_b64 exec, exec, s[0:1]
	s_add_i32 s16, s16, 4
	s_cmp_ge_i32 s12, s16
	s_waitcnt lgkmcnt(0)
	s_barrier
	s_cbranch_scc1 .LBB0_539
	v_add_f32_e32 v4, v9, v10
	v_or_b32_e32 v94, s14, v3
	v_lshlrev_b32_e32 v102, 2, v7
	v_lshrrev_b32_e32 v3, 2, v1
	v_mul_f32_e32 v100, 0x3fb8aa3b, v4
	v_and_or_b32 v3, v3, 3, v102
	s_movk_i32 s0, 0xa0
	v_lshlrev_b32_e32 v4, 1, v8
	v_lshlrev_b32_e32 v5, 3, v8
	v_lshl_add_u32 v98, v7, 4, 0
	v_mad_u32_u24 v3, v3, s0, 0
	v_and_b32_e32 v4, 32, v4
	v_and_b32_e32 v5, 24, v5
	v_mov_b32_e32 v14, v0
	v_mov_b32_e32 v15, v0
	v_sub_u32_e32 v99, v92, v6
	v_add3_u32 v104, v3, v4, v5
	v_mad_u32_u24 v105, v6, s25, v98
	v_add_u32_e32 v106, 64, v1
	v_add_u32_e32 v107, 64, v2
	v_mov_b32_e32 v1, v0
	v_mov_b32_e32 v2, v0
	v_mov_b32_e32 v3, v0
	v_mov_b32_e32 v4, v0
	v_mov_b32_e32 v5, v0
	v_mov_b32_e32 v6, v0
	v_mov_b32_e32 v7, v0
	v_mov_b32_e32 v8, v0
	v_mov_b32_e32 v9, v0
	v_mov_b32_e32 v10, v0
	v_mov_b32_e32 v11, v0
	v_mov_b32_e32 v12, v0
	v_mov_b32_e32 v13, v0
	v_mov_b64_e32 v[32:33], v[14:15]
	s_add_i32 s15, s12, s15
	v_mov_b64_e32 v[30:31], v[12:13]
	v_mov_b64_e32 v[28:29], v[10:11]
	v_mov_b64_e32 v[26:27], v[8:9]
	v_mov_b64_e32 v[24:25], v[6:7]
	v_mov_b64_e32 v[22:23], v[4:5]
	v_mov_b64_e32 v[20:21], v[2:3]
	v_mov_b64_e32 v[18:19], v[0:1]
	v_mov_b64_e32 v[16:17], v[14:15]
	v_add_u32_e32 v101, 31, v99
	s_add_i32 s15, s15, 1
	s_mov_b32 s17, 0
	v_mov_b32_e32 v108, 0xff800000
	v_mov_b32_e32 v103, 0
	v_mov_b64_e32 v[14:15], v[12:13]
	v_mov_b64_e32 v[12:13], v[10:11]
	v_mov_b64_e32 v[10:11], v[8:9]
	v_mov_b64_e32 v[8:9], v[6:7]
	v_mov_b64_e32 v[6:7], v[4:5]
	v_mov_b64_e32 v[4:5], v[2:3]
	v_mov_b64_e32 v[2:3], v[0:1]
	v_mov_b32_e32 v1, 0
	v_readlane_b32 s100, v254, 21
	s_nop 3
	s_lshr_b32 s100, s100, 2
	s_cmp_eq_u32 s100, 1
	s_cbranch_scc0 .Lpa_noprio
	s_setprio 1
.Lpa_noprio:
	v_readlane_b32 s98, v254, 21
	s_nop 3
	s_lshr_b32 s98, s98, 2
	s_mul_i32 s101, s98, 0x1200
	v_subrev_u32_e32 v156, s101, v91
	s_mul_i32 s101, s98, 0x1400
	v_subrev_u32_e32 v157, s101, v95
	s_lshl_b32 s101, s98, 5
	v_subrev_u32_e32 v158, s101, v107
	v_add_u32_e32 v158, 64, v158
	s_mov_b32 s99, 0
	s_cmp_eq_u32 s98, 0
	s_cbranch_scc1 .Lpa_pre_done
	s_add_i32 s100, s12, 1
	s_cmp_ge_i32 s100, s16
	s_cbranch_scc1 .Lpa_pre_done
	v_add_u32_e32 v34, s13, v158
	v_add_u32_e32 v34, 0xffffffc0, v34
	v_ashrrev_i32_e32 v35, 31, v34
	v_lshlrev_b64 v[34:35], 11, v[34:35]
	v_lshl_or_b32 v34, v94, 1, v34
	v_lshl_add_u64 v[36:37], s[38:39], 0, v[34:35]
	v_lshl_add_u64 v[34:35], s[40:41], 0, v[34:35]
	s_mov_b64 s[100:101], 0x10000
	global_load_dwordx4 v[140:143], v[36:37], off
	global_load_dwordx4 v[148:151], v[34:35], off
	v_lshl_add_u64 v[36:37], v[36:37], 0, s[100:101]
	v_lshl_add_u64 v[34:35], v[34:35], 0, s[100:101]
	global_load_dwordx4 v[144:147], v[36:37], off
	global_load_dwordx4 v[152:155], v[34:35], off

; __device__ __forceinline__ unsigned cvt_pk_bf16(float lo, float hi) { unsigned r; asm volatile("v_cvt_pk_bf16_f32 %0, %1, %2" : "=v"(r) : "v"(lo), "v"(hi)); return r; }
; __device__ __forceinline__ void attn_unit(const Args& a, LAS unsigned char* lds, const int mode, const int h, const int qb, const int tid_in, const int lane_in, const int wave) {
;     ...
;     if (active) {
;         const float lt = l_run + __shfl_xor(l_run, 32); const float rl = 1.0f / lt;
;         bf16_t* Y = (bf16_t*)(ws + WS_YCAT) + (size_t)qrow * (2 * D) + D + h * HD;
; #pragma unroll
;         for (int g = 0; g < 4; ++g) {
;             u32x2 w0, w1; w0.x = cvt_pk_bf16(o0[4 * g] * rl, o0[4 * g + 1] * rl); w0.y = cvt_pk_bf16(o0[4 * g + 2] * rl, o0[4 * g + 3] * rl);
;             w1.x = cvt_pk_bf16(o1[4 * g] * rl, o1[4 * g + 1] * rl); w1.y = cvt_pk_bf16(o1[4 * g + 2] * rl, o1[4 * g + 3] * rl);
;             *(u32x2*)(Y + 8 * g + 4 * hi) = w0; *(u32x2*)(Y + 32 + 8 * g + 4 * hi) = w1; }
.LBB0_540:
	s_setprio 0
	v_readlane_b32 s0, v254, 23
	v_readlane_b32 s1, v254, 24
	s_and_b64 vcc, exec, s[0:1]
	s_cbranch_vccz .LBB0_542
	v_and_b32_e32 v34, 64, v138
	v_xor_b32_e32 v1, 32, v138
	v_add_u32_e32 v34, 64, v34
	v_cmp_lt_i32_e32 vcc, v1, v34
	v_lshlrev_b64 v[34:35], 12, v[92:93]
	v_lshl_add_u64 v[34:35], s[88:89], 0, v[34:35]
	v_cndmask_b32_e32 v1, v138, v1, vcc
	v_lshlrev_b32_e32 v1, 2, v1
	ds_bpermute_b32 v1, v1, v103
	s_lshl_b32 s72, s14, 1
	v_lshl_add_u64 v[34:35], v[34:35], 0, s[72:73]
	v_mov_b32_e32 v91, v0
	v_lshl_add_u64 v[34:35], v[34:35], 0, v[90:91]
	s_waitcnt lgkmcnt(0)
	v_add_f32_e32 v1, v103, v1
	v_div_scale_f32 v36, s[0:1], v1, v1, 1.0
	v_rcp_f32_e32 v37, v36
	v_div_scale_f32 v38, vcc, 1.0, v1, 1.0
	s_mov_b64 s[0:1], 0x14000800
	v_fma_f32 v39, -v36, v37, 1.0
	v_fmac_f32_e32 v37, v39, v37
	v_mul_f32_e32 v39, v38, v37
	v_fma_f32 v40, -v36, v39, v38
	v_fmac_f32_e32 v39, v40, v37
	v_fma_f32 v36, -v36, v39, v38
	v_div_fmas_f32 v36, v36, v37, v39
	v_div_fixup_f32 v1, v36, v1, 1.0
	v_mul_f32_e32 v18, v18, v1
	v_mul_f32_e32 v19, v19, v1
	v_cvt_pk_bf16_f32 v18, v18, v19
	v_mul_f32_e32 v19, v20, v1
	v_mul_f32_e32 v2, v2, v1
	v_mul_f32_e32 v3, v3, v1
	v_lshl_add_u64 v[36:37], v[34:35], 0, s[0:1]
	v_mul_f32_e32 v20, v21, v1
	v_cvt_pk_bf16_f32 v19, v19, v20
	v_cvt_pk_bf16_f32 v2, v2, v3
	v_mul_f32_e32 v3, v4, v1
	v_mul_f32_e32 v4, v5, v1
	s_brev_b32 s0, 40
	v_cvt_pk_bf16_f32 v3, v3, v4
	v_add_co_u32_e32 v4, vcc, s0, v34
	s_nop 1
	v_addc_co_u32_e32 v5, vcc, 0, v35, vcc
	global_store_dwordx2 v[4:5], v[18:19], off offset:2048
	global_store_dwordx2 v[36:37], v[2:3], off offset:64
	v_mul_f32_e32 v2, v22, v1
	v_mul_f32_e32 v3, v23, v1
	v_cvt_pk_bf16_f32 v2, v2, v3
	v_mul_f32_e32 v3, v24, v1
	v_mul_f32_e32 v4, v25, v1
	v_cvt_pk_bf16_f32 v3, v3, v4
	v_mul_f32_e32 v4, v6, v1
	v_mul_f32_e32 v5, v7, v1
	v_cvt_pk_bf16_f32 v4, v4, v5
	v_mul_f32_e32 v5, v8, v1
	v_mul_f32_e32 v6, v9, v1
	v_cvt_pk_bf16_f32 v5, v5, v6
	global_store_dwordx2 v[36:37], v[2:3], off offset:16
	global_store_dwordx2 v[36:37], v[4:5], off offset:80
	v_mul_f32_e32 v2, v26, v1
	v_mul_f32_e32 v3, v27, v1
	v_cvt_pk_bf16_f32 v2, v2, v3
	v_mul_f32_e32 v3, v28, v1
	v_mul_f32_e32 v4, v29, v1
	v_cvt_pk_bf16_f32 v3, v3, v4
	v_mul_f32_e32 v4, v10, v1
	v_mul_f32_e32 v5, v11, v1
	v_cvt_pk_bf16_f32 v4, v4, v5
	v_mul_f32_e32 v5, v12, v1
	v_mul_f32_e32 v6, v13, v1
	v_cvt_pk_bf16_f32 v5, v5, v6
	global_store_dwordx2 v[36:37], v[2:3], off offset:32
	global_store_dwordx2 v[36:37], v[4:5], off offset:96
	v_mul_f32_e32 v2, v30, v1
	v_mul_f32_e32 v3, v31, v1
	v_cvt_pk_bf16_f32 v2, v2, v3
	v_mul_f32_e32 v3, v32, v1
	v_mul_f32_e32 v4, v33, v1
	v_cvt_pk_bf16_f32 v3, v3, v4
	v_mul_f32_e32 v4, v14, v1
	v_mul_f32_e32 v5, v15, v1
	v_cvt_pk_bf16_f32 v4, v4, v5
	v_mul_f32_e32 v5, v16, v1
	v_mul_f32_e32 v1, v17, v1
	v_cvt_pk_bf16_f32 v5, v5, v1
	global_store_dwordx2 v[36:37], v[2:3], off offset:48
	global_store_dwordx2 v[36:37], v[4:5], off offset:112
	s_cbranch_execnz .LBB0_397
	s_branch .LBB0_543
